# queue ticket wait deferred to item end; SWA epilogue gate loads batched (both copies); GDN gate params via scalar loads
# speedup vs baseline: 1.0072x; 1.0072x over previous
; DI unsigned xb_add(unsigned* p, unsigned v) { return __hip_atomic_fetch_add(p, v, __ATOMIC_RELAXED, __HIP_MEMORY_SCOPE_AGENT); }
; #define ITEM_BEGIN { size_t z_ = 0; asm volatile("" : "+s"(z_)); q.ws = p.ws + z_; sm = smem + osgpr(0); }
; __global__ __launch_bounds__(512, 2) void mega(P p) {
;     ...
;             if (threadIdx.x == 0) qw[0] = xb_add(qctr, 1u);
;             __syncthreads();
;             int it = (int)qw[0];
;             __syncthreads();
;             while (it < ntot) {
;                 ITEM_BEGIN
;                 if (threadIdx.x == 0) nxt = xb_add(qctr, 1u);
.LBB0_242:
	s_mov_b64 s[0:1], 0
	s_mov_b32 s45, s19
	s_mov_b64 s[36:37], exec
	v_readlane_b32 s2, v253, 1
	v_readlane_b32 s3, v253, 2
	s_and_b64 s[2:3], s[36:37], s[2:3]
	s_mov_b64 exec, s[2:3]
	s_cbranch_execz .LBB0_246
	s_mov_b64 s[40:41], exec
	v_mbcnt_lo_u32_b32 v0, s40, 0
	v_mbcnt_hi_u32_b32 v0, s41, v0
	v_cmp_eq_u32_e32 vcc, 0, v0
	s_and_saveexec_b64 s[38:39], vcc
	s_cbranch_execz .LBB0_245
	s_bcnt1_i32_b64 s2, s[40:41]
	v_mov_b32_e32 v1, s2
	v_readlane_b32 s2, v254, 60
	v_readlane_b32 s3, v254, 61
	s_nop 4
	global_atomic_add v111, v133, v1, s[2:3] sc0
.LBB0_245:
	s_or_b64 exec, exec, s[38:39]
; DI void unpack8(u32x4 v, float* o) { o[0] = lo16(v.x); o[1] = hi16(v.x); o[2] = lo16(v.y); o[3] = hi16(v.y); o[4] = lo16(v.z); o[5] = hi16(v.z); o[6] = lo16(v.w); o[7] = hi16(v.w); }
; DI u32x4 pack8(const float* o) { u32x4 r; r.x = pk2(o[0], o[1]); r.y = pk2(o[2], o[3]); r.z = pk2(o[4], o[5]); r.w = pk2(o[6], o[7]); return r; }
; DI int otid() { int t = threadIdx.x; asm volatile("" : "+v"(t)); return t; }
; DI unsigned xb_add(unsigned* p, unsigned v) { return __hip_atomic_fetch_add(p, v, __ATOMIC_RELAXED, __HIP_MEMORY_SCOPE_AGENT); }
; DI void krope_item(const P& p, int r32) {
;     const bf16_t* S = (const bf16_t*)(p.ws + WS_SBUF);
;     bf16_t* KR = (bf16_t*)(p.ws + WS_KR);
;     const int tid = otid(); const int row = r32 * 32 + (tid >> 4), u = tid & 15, hk = u >> 3, hf = (u >> 2) & 1, e8 = (u & 3) * 8;
;     const bf16_t* src = S + (size_t)row * NP + C_SWA_K + 128 * hk + 64 * hf + e8;
;     float x1[8], x2[8]; unpack8(__builtin_nontemporal_load((const u32x4*)src), x1); unpack8(__builtin_nontemporal_load((const u32x4*)(src + 32)), x2);
;     const int kp = row & 2047;
;     rope8(x1, x2, e8, (float)(hf == 0 ? (kp >> 6) : (kp & 63)));
;     bf16_t* dst = KR + (size_t)row * 256 + 128 * hk + 64 * hf + e8;
;     *(u32x4*)dst = pack8(x1); *(u32x4*)(dst + 32) = pack8(x2);
; }
; __global__ __launch_bounds__(512, 2) void mega(P p) {
;     ...
;                 if (threadIdx.x == 0) nxt = xb_add(qctr, 1u);
;                 if (it < 576) { for (int r2 = 0; r2 < REP_GDNP; ++r2) gdn_prep_item(q, l, it, sm); }
;                 else if (it < 576 + 576) { for (int r2 = 0; r2 < REP_GLAP; ++r2) gla_prep_item(q, l, it - 576, sm); }
;                 else if (it < 576 + 576 + nconv) conv_item(q, l, it - 576 - 576);
;                 else krope_item(q, it - 576 - 576 - nconv);
.LBB0_246:
	s_or_b64 exec, exec, s[36:37]
	v_readlane_b32 s4, v254, 26
	v_readlane_b32 s5, v254, 27
	s_add_u32 s42, s4, s0
	s_addc_u32 s43, s5, s1
	s_add_i32 s26, s45, 0
	s_cmpk_gt_i32 s28, 0x23f
	s_mov_b64 s[0:1], -1
	v_readlane_b32 s6, v254, 28
	v_readlane_b32 s7, v254, 29
	s_cbranch_scc0 .LBB0_266
	s_cmpk_gt_u32 s28, 0x47f
	s_cbranch_scc0 .LBB0_253
	v_readlane_b32 s0, v252, 3
	s_cmp_ge_i32 s28, s0
	s_mov_b64 s[0:1], -1
	s_cbranch_scc0 .LBB0_250
	v_readlane_b32 s0, v252, 4
	v_mov_b32_e32 v2, v166
	s_add_i32 s0, s0, s28
	v_mov_b32_e32 v11, v133
	v_ashrrev_i32_e32 v0, 4, v2
	v_lshl_add_u32 v8, s0, 5, v0
	v_lshlrev_b32_e32 v0, 3, v2
	v_bfe_u32 v14, v2, 2, 1
	v_and_b32_e32 v26, 24, v0
	v_mov_b64_e32 v[0:1], s[42:43]
	s_movk_i32 s0, 0x3800
	v_lshlrev_b32_e32 v2, 5, v2
	v_mad_i64_i32 v[0:1], s[0:1], v8, s0, v[0:1]
	v_and_b32_e32 v132, 0x100, v2
	v_lshl_add_u64 v[0:1], v[0:1], 0, v[132:133]
	v_lshlrev_b32_e32 v10, 7, v14
	v_lshl_add_u64 v[0:1], v[0:1], 0, v[10:11]
	v_lshlrev_b32_e32 v12, 1, v26
	v_mov_b32_e32 v13, v133
	v_lshl_add_u64 v[0:1], v[0:1], 0, v[12:13]
	s_mov_b64 s[0:1], 0x6c3f000
	v_lshl_add_u64 v[4:5], v[0:1], 0, s[0:1]
	s_mov_b32 s0, 0x6c3f000
	v_add_co_u32_e32 v0, vcc, s0, v0
	v_cvt_f32_ubyte0_e32 v17, v26
	s_nop 0
	v_addc_co_u32_e32 v1, vcc, 0, v1, vcc
	v_mul_f32_e32 v18, 0xbed49a78, v17
	s_mov_b32 s2, 0xc2fc0000
	v_cmp_gt_f32_e32 vcc, s2, v18
	v_bfe_u32 v15, v8, 6, 5
	v_and_b32_e32 v16, 63, v8
	v_cndmask_b32_e32 v18, 0, v170, vcc
	v_fmac_f32_e32 v18, 0xbed49a78, v17
	v_exp_f32_e32 v17, v18
	v_cmp_eq_u32_e64 s[0:1], 0, v14
	global_load_dwordx4 v[0:3], v[0:1], off nt
	s_nop 0
	global_load_dwordx4 v[4:7], v[4:5], off offset:64 nt
	v_cndmask_b32_e64 v14, v16, v15, s[0:1]
	v_cvt_f32_ubyte0_e32 v27, v14
	v_cndmask_b32_e32 v14, 0, v171, vcc
	v_ldexp_f32 v14, v17, v14
	v_mul_f32_e32 v14, v14, v27
	v_mul_f32_e32 v15, 0.15915494, v14
	v_or_b32_e32 v14, 1, v26
	v_cvt_f32_ubyte0_e32 v14, v14
	v_mul_f32_e32 v16, 0xbed49a78, v14
	v_cmp_gt_f32_e32 vcc, s2, v16
	v_ashrrev_i32_e32 v9, 31, v8
	v_lshlrev_b64 v[8:9], 9, v[8:9]
	v_cndmask_b32_e32 v16, 0, v170, vcc
	v_fmac_f32_e32 v16, 0xbed49a78, v14
	v_exp_f32_e32 v17, v16
	v_sin_f32_e32 v14, v15
	v_cos_f32_e32 v16, v15
	v_cndmask_b32_e32 v15, 0, v171, vcc
	v_ldexp_f32 v15, v17, v15
	v_mul_f32_e32 v15, v15, v27
	v_mul_f32_e32 v17, 0.15915494, v15
	v_or_b32_e32 v15, 2, v26
	v_cvt_f32_ubyte0_e32 v15, v15
	v_mul_f32_e32 v18, 0xbed49a78, v15
	v_cmp_gt_f32_e32 vcc, s2, v18
	v_lshl_add_u64 v[8:9], s[42:43], 0, v[8:9]
	v_lshl_add_u64 v[8:9], v[8:9], 0, v[132:133]
	v_cndmask_b32_e32 v18, 0, v170, vcc
	v_fmac_f32_e32 v18, 0xbed49a78, v15
	v_exp_f32_e32 v18, v18
	v_cndmask_b32_e32 v19, 0, v171, vcc
	v_sin_f32_e32 v15, v17
	v_cos_f32_e32 v17, v17
	v_ldexp_f32 v18, v18, v19
	v_mul_f32_e32 v18, v18, v27
	v_mul_f32_e32 v19, 0.15915494, v18
	v_or_b32_e32 v18, 3, v26
	v_cvt_f32_ubyte0_e32 v18, v18
	v_mul_f32_e32 v20, 0xbed49a78, v18
	v_cmp_gt_f32_e32 vcc, s2, v20
	v_lshl_add_u64 v[8:9], v[8:9], 0, v[10:11]
	v_lshl_add_u64 v[8:9], v[8:9], 0, v[12:13]
	v_cndmask_b32_e32 v20, 0, v170, vcc
	v_fmac_f32_e32 v20, 0xbed49a78, v18
	v_exp_f32_e32 v21, v20
	v_sin_f32_e32 v18, v19
	v_cos_f32_e32 v20, v19
	v_cndmask_b32_e32 v19, 0, v171, vcc
	v_ldexp_f32 v19, v21, v19
	v_mul_f32_e32 v19, v19, v27
	v_mul_f32_e32 v21, 0.15915494, v19
	v_or_b32_e32 v19, 4, v26
	v_cvt_f32_ubyte0_e32 v19, v19
	v_mul_f32_e32 v22, 0xbed49a78, v19
	v_cmp_gt_f32_e32 vcc, s2, v22
	s_mov_b64 s[0:1], 0x1805d200
	v_lshl_add_u64 v[10:11], v[8:9], 0, s[0:1]
	v_cndmask_b32_e32 v22, 0, v170, vcc
	v_fmac_f32_e32 v22, 0xbed49a78, v19
	v_exp_f32_e32 v22, v22
	v_cndmask_b32_e32 v23, 0, v171, vcc
	v_sin_f32_e32 v19, v21
	v_cos_f32_e32 v21, v21
	v_ldexp_f32 v22, v22, v23
	v_mul_f32_e32 v22, v22, v27
	v_mul_f32_e32 v23, 0.15915494, v22
	v_or_b32_e32 v22, 5, v26
	v_cvt_f32_ubyte0_e32 v22, v22
	v_mul_f32_e32 v24, 0xbed49a78, v22
	v_cmp_gt_f32_e32 vcc, s2, v24
	s_mov_b32 s0, 0x1805d000
	s_waitcnt vmcnt(1)
	v_lshlrev_b32_e32 v12, 16, v0
	v_cndmask_b32_e32 v24, 0, v170, vcc
	v_fmac_f32_e32 v24, 0xbed49a78, v22
	v_exp_f32_e32 v25, v24
	v_sin_f32_e32 v22, v23
	v_cos_f32_e32 v24, v23
	v_cndmask_b32_e32 v23, 0, v171, vcc
	v_ldexp_f32 v23, v25, v23
	v_mul_f32_e32 v23, v23, v27
	v_mul_f32_e32 v25, 0.15915494, v23
	v_or_b32_e32 v23, 6, v26
	v_cvt_f32_ubyte0_e32 v23, v23
	v_mul_f32_e32 v28, 0xbed49a78, v23
	v_cmp_gt_f32_e32 vcc, s2, v28
	v_or_b32_e32 v26, 7, v26
	v_cvt_f32_ubyte0_e32 v26, v26
	v_cndmask_b32_e32 v28, 0, v170, vcc
	v_fmac_f32_e32 v28, 0xbed49a78, v23
	v_exp_f32_e32 v28, v28
	v_cndmask_b32_e32 v29, 0, v171, vcc
	s_waitcnt vmcnt(0)
	v_and_b32_e32 v31, 0xffff0000, v4
	v_sin_f32_e32 v23, v25
	v_ldexp_f32 v28, v28, v29
	v_mul_f32_e32 v29, 0xbed49a78, v26
	v_cmp_gt_f32_e32 vcc, s2, v29
	v_mul_f32_e32 v28, v28, v27
	v_and_b32_e32 v13, 0xffff0000, v0
	v_cndmask_b32_e32 v29, 0, v170, vcc
	v_fmac_f32_e32 v29, 0xbed49a78, v26
	v_exp_f32_e32 v29, v29
	v_cndmask_b32_e32 v30, 0, v171, vcc
	v_cos_f32_e32 v25, v25
	v_mul_f32_e32 v28, 0.15915494, v28
	v_ldexp_f32 v29, v29, v30
	v_lshlrev_b32_e32 v30, 16, v4
	v_mul_f32_e32 v27, v29, v27
	v_pk_mul_f32 v[32:33], v[14:15], v[30:31]
	v_mul_f32_e32 v29, 0.15915494, v27
	v_pk_fma_f32 v[32:33], v[16:17], v[12:13], v[32:33] neg_lo:[0,0,1] neg_hi:[0,0,1]
	v_lshlrev_b32_e32 v4, 16, v5
	v_and_b32_e32 v5, 0xffff0000, v5
	v_sin_f32_e32 v26, v28
	v_sin_f32_e32 v27, v29
	v_cvt_pk_bf16_f32 v0, v32, v33
	v_lshlrev_b32_e32 v32, 16, v1
	v_and_b32_e32 v33, 0xffff0000, v1
	v_pk_mul_f32 v[34:35], v[18:19], v[4:5]
	v_cos_f32_e32 v28, v28
	v_cos_f32_e32 v29, v29
	v_pk_fma_f32 v[34:35], v[20:21], v[32:33], v[34:35] neg_lo:[0,0,1] neg_hi:[0,0,1]
	v_lshlrev_b32_e32 v36, 16, v6
	v_and_b32_e32 v37, 0xffff0000, v6
	v_cvt_pk_bf16_f32 v1, v34, v35
	v_lshlrev_b32_e32 v34, 16, v2
	v_and_b32_e32 v35, 0xffff0000, v2
	v_pk_mul_f32 v[38:39], v[22:23], v[36:37]
	v_lshlrev_b32_e32 v6, 16, v7
	v_pk_fma_f32 v[38:39], v[24:25], v[34:35], v[38:39] neg_lo:[0,0,1] neg_hi:[0,0,1]
	v_and_b32_e32 v7, 0xffff0000, v7
	v_cvt_pk_bf16_f32 v2, v38, v39
	v_lshlrev_b32_e32 v38, 16, v3
	v_and_b32_e32 v39, 0xffff0000, v3
	v_pk_mul_f32 v[40:41], v[26:27], v[6:7]
	v_add_co_u32_e32 v8, vcc, s0, v8
	v_pk_fma_f32 v[40:41], v[28:29], v[38:39], v[40:41] neg_lo:[0,0,1] neg_hi:[0,0,1]
	s_nop 0
	v_addc_co_u32_e32 v9, vcc, 0, v9, vcc
	v_cvt_pk_bf16_f32 v3, v40, v41
	global_store_dwordx4 v[8:9], v[0:3], off offset:512
	s_mov_b64 s[0:1], 0
	s_nop 0
	v_pk_mul_f32 v[0:1], v[16:17], v[30:31]
	v_pk_mul_f32 v[2:3], v[20:21], v[4:5]
	v_pk_fma_f32 v[0:1], v[14:15], v[12:13], v[0:1]
	v_pk_fma_f32 v[2:3], v[18:19], v[32:33], v[2:3]
	v_cvt_pk_bf16_f32 v0, v0, v1
	v_cvt_pk_bf16_f32 v1, v2, v3
	v_pk_mul_f32 v[2:3], v[24:25], v[36:37]
	v_pk_mul_f32 v[4:5], v[28:29], v[6:7]
	v_pk_fma_f32 v[2:3], v[22:23], v[34:35], v[2:3]
	v_pk_fma_f32 v[4:5], v[26:27], v[38:39], v[4:5]
	v_cvt_pk_bf16_f32 v2, v2, v3
	v_cvt_pk_bf16_f32 v3, v4, v5
	global_store_dwordx4 v[10:11], v[0:3], off offset:64

; DI void gdn_prep_item(const P& p, int l, int item, unsigned char* smem) {
;     ...
;     if (sub == 0) {
;         const float a_in = dir ? a_raw1 : a_raw0, b_in = dir ? b_raw1 : b_raw0;
;         const float A = __expf(p.gdn_alog[(l * 2 + dir) * 4 + h]);
;         const float xx = a_in + p.gdn_dtb[(l * 2 + dir) * 4 + h];
;         const float sp = fmaxf(xx, 0.f) + log1pf(__expf(-fabsf(xx)));
;         sg[i] = -A * sp; sbeta[i] = __builtin_amdgcn_rcpf(1.f + __expf(-b_in));
;     }
.LBB0_322:
	v_cndmask_b32_e64 v16, v103, v91, s[36:37]
	v_lshlrev_b32_e32 v18, 2, v16
	v_add_u32_e32 v17, s44, v18
	s_and_saveexec_b64 s[82:83], s[0:1]
	s_cbranch_execz .LBB0_324
	s_lshl_b32 s2, s31, 2
	s_or_b32 s2, s2, s30
	s_ashr_i32 s3, s2, 31
	s_mov_b32 s89, s19
	s_lshl_b64 s[2:3], s[2:3], 2
	v_readlane_b32 s12, v254, 47
	v_readlane_b32 s13, v254, 48
	s_add_u32 s12, s12, s2
	s_addc_u32 s13, s13, s3
	s_load_dword s4, s[12:13], 0x0
	v_readlane_b32 s14, v254, 49
	v_readlane_b32 s15, v254, 50
	s_add_u32 s2, s14, s2
	s_addc_u32 s3, s15, s3
	s_load_dword s5, s[2:3], 0x0
	s_waitcnt vmcnt(2)
	v_cndmask_b32_e64 v20, v95, v93, s[36:37]
	s_waitcnt vmcnt(0)
	v_cndmask_b32_e64 v19, v99, v97, s[36:37]
	v_mul_f32_e32 v19, 0xbfb8aa3b, v19
	v_exp_f32_e32 v19, v19
	v_readlane_b32 s16, v254, 51
	v_readlane_b32 s19, v254, 54
	s_mov_b32 s19, s89
	v_add_f32_e32 v19, 1.0, v19
	v_rcp_f32_e32 v19, v19
	s_mov_b32 s16, s29
	v_readlane_b32 s6, v254, 41
	v_readlane_b32 s7, v254, 42
	v_readlane_b32 s8, v254, 43
	v_readlane_b32 s9, v254, 44
	v_readlane_b32 s10, v254, 45
	v_readlane_b32 s11, v254, 46
	v_readlane_b32 s17, v254, 52
	v_readlane_b32 s18, v254, 53
	ds_write_b32 v17, v19
	s_waitcnt lgkmcnt(0)
	v_mov_b32_e32 v21, s4
	v_mul_f32_e32 v21, 0x3fb8aa3b, v21
	v_exp_f32_e32 v22, v21
	v_mov_b32_e32 v21, s5
	s_mov_b32 s2, 0xbfb8aa3b
	v_add_f32_e32 v20, v20, v21
	v_max_f32_e32 v23, 0, v20
	v_mul_f32_e64 v20, |v20|, s2
	v_exp_f32_e32 v24, v20
	s_mov_b32 s2, 0x3f2aaaab
	v_add_f32_e32 v25, 1.0, v24
	v_add_f32_e32 v20, -1.0, v25
	v_sub_f32_e32 v21, v20, v25
	v_add_f32_e32 v21, 1.0, v21
	v_sub_f32_e32 v20, v24, v20
	v_add_f32_e32 v26, v20, v21
	v_frexp_mant_f32_e32 v20, v25
	v_cmp_gt_f32_e32 vcc, s2, v20
	v_cvt_f64_f32_e32 v[20:21], v25
	v_frexp_exp_i32_f64_e32 v20, v[20:21]
	v_subbrev_co_u32_e32 v20, vcc, 0, v20, vcc
	v_sub_u32_e32 v21, 0, v20
	v_ldexp_f32 v25, v25, v21
	v_ldexp_f32 v21, v26, v21
	v_add_f32_e32 v26, -1.0, v25
	v_add_f32_e32 v27, 1.0, v26
	v_sub_f32_e32 v27, v25, v27
	v_add_f32_e32 v27, v21, v27
	v_add_f32_e32 v28, v26, v27
	v_sub_f32_e32 v26, v28, v26
	v_sub_f32_e32 v26, v27, v26
	v_add_f32_e32 v27, 1.0, v25
	v_add_f32_e32 v29, -1.0, v27
	v_sub_f32_e32 v25, v25, v29
	v_add_f32_e32 v21, v21, v25
	v_add_f32_e32 v25, v27, v21
	v_sub_f32_e32 v27, v25, v27
	v_sub_f32_e32 v21, v21, v27
	v_rcp_f32_e32 v27, v25
	v_cvt_f32_i32_e32 v20, v20
	s_mov_b32 s2, 0x3f317218
	v_mul_f32_e32 v29, v28, v27
	v_mul_f32_e32 v30, v25, v29
	v_fma_f32 v31, v29, v25, -v30
	v_fmac_f32_e32 v31, v29, v21
	v_add_f32_e32 v122, v30, v31
	v_sub_f32_e32 v123, v28, v122
	v_sub_f32_e32 v28, v28, v123
	v_sub_f32_e32 v30, v122, v30
	v_sub_f32_e32 v28, v28, v122
	v_add_f32_e32 v26, v26, v28
	v_sub_f32_e32 v28, v30, v31
	v_add_f32_e32 v26, v28, v26
	v_add_f32_e32 v28, v123, v26
	v_mul_f32_e32 v30, v27, v28
	v_mul_f32_e32 v31, v25, v30
	v_fma_f32 v25, v30, v25, -v31
	v_fmac_f32_e32 v25, v30, v21
	v_sub_f32_e32 v21, v123, v28
	v_add_f32_e32 v21, v26, v21
	v_add_f32_e32 v26, v31, v25
	v_sub_f32_e32 v122, v28, v26
	v_sub_f32_e32 v28, v28, v122
	v_sub_f32_e32 v31, v26, v31
	v_sub_f32_e32 v26, v28, v26
	v_add_f32_e32 v21, v21, v26
	v_sub_f32_e32 v25, v31, v25
	v_add_f32_e32 v21, v25, v21
	v_add_f32_e32 v25, v29, v30
	v_add_f32_e32 v21, v122, v21
	v_sub_f32_e32 v26, v25, v29
	v_mul_f32_e32 v21, v27, v21
	v_sub_f32_e32 v26, v30, v26
	v_add_f32_e32 v21, v26, v21
	v_mul_f32_e32 v29, 0x3f317218, v20
	v_add_f32_e32 v26, v25, v21
	v_fma_f32 v30, v20, s2, -v29
	v_mul_f32_e32 v27, v26, v26
	v_mov_b32_e32 v28, 0x3ecc95a3
	v_fmac_f32_e32 v30, 0xb102e308, v20
	v_sub_f32_e32 v20, v26, v25
	v_fmamk_f32 v28, v27, 0x3e9b6dac, v28
	v_sub_f32_e32 v20, v21, v20
	v_add_f32_e32 v21, v29, v30
	v_fmaak_f32 v28, v27, v28, 0x3f2aaada
	v_sub_f32_e32 v25, v21, v29
	v_ldexp_f32 v29, v26, 1
	v_mul_f32_e32 v26, v26, v27
	v_mul_f32_e32 v26, v26, v28
	v_add_f32_e32 v27, v29, v26
	v_sub_f32_e32 v28, v27, v29
	v_ldexp_f32 v20, v20, 1
	v_sub_f32_e32 v26, v26, v28
	v_add_f32_e32 v20, v20, v26
	v_add_f32_e32 v26, v27, v20
	v_sub_f32_e32 v27, v26, v27
	v_sub_f32_e32 v20, v20, v27
	v_add_f32_e32 v27, v21, v26
	v_sub_f32_e32 v28, v27, v21
	v_sub_f32_e32 v29, v27, v28
	v_sub_f32_e32 v25, v30, v25
	v_sub_f32_e32 v21, v21, v29
	v_sub_f32_e32 v26, v26, v28
	v_add_f32_e32 v21, v26, v21
	v_add_f32_e32 v26, v25, v20
	v_sub_f32_e32 v28, v26, v25
	v_sub_f32_e32 v29, v26, v28
	v_sub_f32_e32 v25, v25, v29
	v_sub_f32_e32 v20, v20, v28
	v_add_f32_e32 v21, v26, v21
	v_add_f32_e32 v20, v20, v25
	v_add_f32_e32 v25, v27, v21
	v_sub_f32_e32 v26, v25, v27
	v_sub_f32_e32 v21, v21, v26
	v_add_f32_e32 v20, v20, v21
	s_mov_b32 s2, 0x7f800000
	v_add_f32_e32 v20, v25, v20
	v_cmp_neq_f32_e32 vcc, s2, v24
	v_mov_b32_e32 v21, 0x7f800000
	s_mov_b32 s2, 0x33800000
	v_cndmask_b32_e32 v20, v21, v20, vcc
	v_cmp_ngt_f32_e32 vcc, -1.0, v24
	v_mov_b32_e32 v21, 0x7fc00000
	s_nop 0
	v_cndmask_b32_e32 v20, v21, v20, vcc
	v_cmp_neq_f32_e32 vcc, -1.0, v24
	v_mov_b32_e32 v21, 0xff800000
	s_nop 0
	v_cndmask_b32_e32 v20, v21, v20, vcc
	v_cmp_lt_f32_e64 vcc, |v24|, s2
	v_add_u32_e32 v21, s28, v18
	s_nop 0
	v_cndmask_b32_e32 v20, v20, v24, vcc
	v_add_f32_e32 v20, v23, v20
	v_mul_f32_e64 v20, v20, -v22
	ds_write_b32 v21, v20

; __global__ __launch_bounds__(512, 2) void mega(P p) {
;     ...
;                 if (threadIdx.x == 0) qw[0] = nxt;
;                 __syncthreads();
;                 it = (int)qw[0];
.LBB0_331:
	s_mov_b64 s[0:1], exec
	v_readlane_b32 s2, v253, 1
	v_readlane_b32 s3, v253, 2
	s_and_b64 s[2:3], s[0:1], s[2:3]
	s_mov_b64 exec, s[2:3]
	s_cbranch_execz .LBB0_241
	v_readlane_b32 s2, v254, 34
	s_nop 1
	v_mov_b32_e32 v0, s2
	s_waitcnt vmcnt(0)
	ds_write_b32 v0, v111
	s_branch .LBB0_241

; DI float lo16(unsigned u) { return __uint_as_float(u << 16); }
; DI float hi16(unsigned u) { return __uint_as_float(u & 0xFFFF0000u); }
; DI float siluf(float x) { return x * __builtin_amdgcn_rcpf(1.f + __expf(-x)); }
; DI void swa_item(const P& p, int l, int item, unsigned char* smem) {
;     ...
;     lsum += __shfl_xor(lsum, 16); lsum += __shfl_xor(lsum, 32);
;     const float inv = __builtin_amdgcn_rcpf(lsum);
; #pragma unroll
;     for (int nt = 0; nt < 8; ++nt) {
;         const int dvb = 16 * nt + 4 * g;
;         const u32x2 gw = *(const u32x2*)(S + qrow * NP + C_SWA_G + 128 * hq + dvb);
;         const float g0 = lo16(gw.x), g1 = hi16(gw.x), g2 = lo16(gw.y), g3 = hi16(gw.y);
;         u32x2 o; o.x = pk2(ot[nt][0] * inv * siluf(g0), ot[nt][1] * inv * siluf(g1)); o.y = pk2(ot[nt][2] * inv * siluf(g2), ot[nt][3] * inv * siluf(g3));
;         *(u32x2*)(Y + qrow * DM + 1536 + 128 * hq + dvb) = o;
;     }
.LBB0_390:
	v_cmp_lt_i32_e32 vcc, v107, v109
	s_waitcnt vmcnt(2)
	v_lshlrev_b64 v[34:35], 12, v[96:97]
	v_lshlrev_b64 v[30:31], 1, v[100:101]
	v_cndmask_b32_e32 v28, v105, v107, vcc
	v_lshl_add_u64 v[34:35], s[38:39], 0, v[34:35]
	v_mov_b32_e32 v107, v133
	v_lshl_add_u64 v[32:33], v[98:99], 0, v[30:31]
	v_lshl_add_u64 v[30:31], v[34:35], 0, v[30:31]
	v_lshlrev_b64 v[34:35], 1, v[106:107]
	s_waitcnt vmcnt(1)
	v_lshl_add_u64 v[36:37], v[32:33], 0, v[34:35]
	s_mov_b64 s[0:1], 0x3400
	v_cmp_lt_i32_e32 vcc, v111, v109
	v_lshl_add_u64 v[32:33], v[36:37], 0, s[0:1]
	s_movk_i32 s0, 0x3000
	v_cndmask_b32_e32 v29, v105, v111, vcc
	v_add_co_u32_e32 v36, vcc, s0, v36
	v_lshlrev_b32_e32 v28, 2, v28
	s_nop 0
	v_addc_co_u32_e32 v37, vcc, 0, v37, vcc
	global_load_dwordx2 v[36:37], v[36:37], off offset:1024
	global_load_dwordx2 v[62:63], v[32:33], off offset:32
	global_load_dwordx2 v[64:65], v[32:33], off offset:64
	global_load_dwordx2 v[66:67], v[32:33], off offset:96
	global_load_dwordx2 v[68:69], v[32:33], off offset:128
	global_load_dwordx2 v[70:71], v[32:33], off offset:160
	global_load_dwordx2 v[72:73], v[32:33], off offset:192
	global_load_dwordx2 v[74:75], v[32:33], off offset:224
	ds_bpermute_b32 v28, v28, v119
	v_lshlrev_b32_e32 v29, 2, v29
	v_lshl_add_u64 v[34:35], v[30:31], 0, v[34:35]
	s_mov_b64 s[0:1], 0xea3cc00
	v_lshl_add_u64 v[30:31], v[34:35], 0, s[0:1]
	s_waitcnt lgkmcnt(0)
	v_add_f32_e32 v28, v119, v28
	ds_bpermute_b32 v29, v29, v28
	s_mov_b32 s0, 0xea3c000
	v_add_co_u32_e32 v34, vcc, s0, v34
	v_readlane_b32 s0, v254, 15
	s_waitcnt lgkmcnt(0)
	v_add_f32_e32 v28, v28, v29
	v_rcp_f32_e32 v28, v28
	v_addc_co_u32_e32 v35, vcc, 0, v35, vcc
	s_add_i32 s21, s0, s21
	s_cmp_ge_i32 s21, s13
	s_waitcnt vmcnt(7)
	v_lshlrev_b32_e32 v38, 16, v36
	v_mul_f32_e32 v29, 0xbfb8aa3b, v38
	v_exp_f32_e32 v29, v29
	v_and_b32_e32 v39, 0xffff0000, v36
	v_add_f32_e32 v29, 1.0, v29
	v_rcp_f32_e32 v40, v29
	v_pk_mul_f32 v[42:43], v[48:49], v[28:29] op_sel_hi:[1,0]
	v_mul_f32_e32 v29, 0xbfb8aa3b, v39
	v_exp_f32_e32 v29, v29
	s_nop 0
	v_add_f32_e32 v29, 1.0, v29
	v_rcp_f32_e32 v41, v29
	s_nop 0
	v_pk_mul_f32 v[38:39], v[40:41], v[38:39]
	s_nop 0
	v_pk_mul_f32 v[38:39], v[42:43], v[38:39]
	s_nop 0
	v_cvt_pk_bf16_f32 v36, v38, v39
	v_lshlrev_b32_e32 v38, 16, v37
	v_mul_f32_e32 v29, 0xbfb8aa3b, v38
	v_exp_f32_e32 v29, v29
	v_and_b32_e32 v39, 0xffff0000, v37
	v_add_f32_e32 v29, 1.0, v29
	v_rcp_f32_e32 v40, v29
	v_pk_mul_f32 v[42:43], v[50:51], v[28:29] op_sel_hi:[1,0]
	v_mul_f32_e32 v29, 0xbfb8aa3b, v39
	v_exp_f32_e32 v29, v29
	s_nop 0
	v_add_f32_e32 v29, 1.0, v29
	v_rcp_f32_e32 v41, v29
	s_nop 0
	v_pk_mul_f32 v[38:39], v[40:41], v[38:39]
	s_nop 0
	v_pk_mul_f32 v[38:39], v[42:43], v[38:39]
	s_nop 0
	v_cvt_pk_bf16_f32 v37, v38, v39
	global_store_dwordx2 v[34:35], v[36:37], off offset:3072
	s_waitcnt vmcnt(7)
	v_mov_b32_e32 v34, v62
	v_mov_b32_e32 v35, v63
	v_lshlrev_b32_e32 v36, 16, v34
	v_mul_f32_e32 v29, 0xbfb8aa3b, v36
	v_exp_f32_e32 v29, v29
	v_and_b32_e32 v37, 0xffff0000, v34
	v_lshlrev_b32_e32 v34, 16, v35
	v_and_b32_e32 v35, 0xffff0000, v35
	v_add_f32_e32 v29, 1.0, v29
	v_rcp_f32_e32 v38, v29
	v_pk_mul_f32 v[24:25], v[24:25], v[28:29] op_sel_hi:[1,0]
	v_mul_f32_e32 v29, 0xbfb8aa3b, v37
	v_exp_f32_e32 v29, v29
	s_nop 0
	v_add_f32_e32 v29, 1.0, v29
	v_rcp_f32_e32 v39, v29
	v_pk_mul_f32 v[26:27], v[26:27], v[28:29] op_sel_hi:[1,0]
	v_pk_mul_f32 v[20:21], v[20:21], v[28:29] op_sel_hi:[1,0]
	v_pk_mul_f32 v[22:23], v[22:23], v[28:29] op_sel_hi:[1,0]
	v_pk_mul_f32 v[36:37], v[38:39], v[36:37]
	v_pk_mul_f32 v[16:17], v[16:17], v[28:29] op_sel_hi:[1,0]
	v_pk_mul_f32 v[24:25], v[24:25], v[36:37]
	v_pk_mul_f32 v[18:19], v[18:19], v[28:29] op_sel_hi:[1,0]
	v_cvt_pk_bf16_f32 v24, v24, v25
	v_mul_f32_e32 v25, 0xbfb8aa3b, v34
	v_exp_f32_e32 v25, v25
	v_pk_mul_f32 v[12:13], v[12:13], v[28:29] op_sel_hi:[1,0]
	v_pk_mul_f32 v[14:15], v[14:15], v[28:29] op_sel_hi:[1,0]
	v_pk_mul_f32 v[8:9], v[8:9], v[28:29] op_sel_hi:[1,0]
	v_add_f32_e32 v25, 1.0, v25
	v_rcp_f32_e32 v36, v25
	v_mul_f32_e32 v25, 0xbfb8aa3b, v35
	v_exp_f32_e32 v25, v25
	v_pk_mul_f32 v[10:11], v[10:11], v[28:29] op_sel_hi:[1,0]
	v_pk_mul_f32 v[4:5], v[4:5], v[28:29] op_sel_hi:[1,0]
	v_pk_mul_f32 v[6:7], v[6:7], v[28:29] op_sel_hi:[1,0]
	v_add_f32_e32 v25, 1.0, v25
	v_rcp_f32_e32 v37, v25
	v_pk_mul_f32 v[0:1], v[0:1], v[28:29] op_sel_hi:[1,0]
	v_pk_mul_f32 v[2:3], v[2:3], v[28:29] op_sel_hi:[1,0]
	v_pk_mul_f32 v[34:35], v[36:37], v[34:35]
	s_nop 0
	v_pk_mul_f32 v[26:27], v[26:27], v[34:35]
	s_nop 0
	v_cvt_pk_bf16_f32 v25, v26, v27
	global_store_dwordx2 v[30:31], v[24:25], off offset:32
	s_waitcnt vmcnt(7)
	v_mov_b32_e32 v24, v64
	v_mov_b32_e32 v25, v65
	v_lshlrev_b32_e32 v26, 16, v24
	v_and_b32_e32 v27, 0xffff0000, v24
	v_mul_f32_e32 v24, 0xbfb8aa3b, v26
	v_exp_f32_e32 v24, v24
	s_nop 0
	v_add_f32_e32 v24, 1.0, v24
	v_rcp_f32_e32 v34, v24
	v_mul_f32_e32 v24, 0xbfb8aa3b, v27
	v_exp_f32_e32 v24, v24
	s_nop 0
	v_add_f32_e32 v24, 1.0, v24
	v_rcp_f32_e32 v35, v24
	v_lshlrev_b32_e32 v24, 16, v25
	v_and_b32_e32 v25, 0xffff0000, v25
	v_pk_mul_f32 v[26:27], v[34:35], v[26:27]
	s_nop 0
	v_pk_mul_f32 v[20:21], v[20:21], v[26:27]
	s_nop 0
	v_cvt_pk_bf16_f32 v20, v20, v21
	v_mul_f32_e32 v21, 0xbfb8aa3b, v24
	v_exp_f32_e32 v21, v21
	s_nop 0
	v_add_f32_e32 v21, 1.0, v21
	v_rcp_f32_e32 v26, v21
	v_mul_f32_e32 v21, 0xbfb8aa3b, v25
	v_exp_f32_e32 v21, v21
	s_nop 0
	v_add_f32_e32 v21, 1.0, v21
	v_rcp_f32_e32 v27, v21
	s_nop 0
	v_pk_mul_f32 v[24:25], v[26:27], v[24:25]
	s_nop 0
	v_pk_mul_f32 v[22:23], v[22:23], v[24:25]
	s_nop 0
	v_cvt_pk_bf16_f32 v21, v22, v23
	global_store_dwordx2 v[30:31], v[20:21], off offset:64
	s_waitcnt vmcnt(7)
; DI float lo16(unsigned u) { return __uint_as_float(u << 16); }
; DI float hi16(unsigned u) { return __uint_as_float(u & 0xFFFF0000u); }
; DI float siluf(float x) { return x * __builtin_amdgcn_rcpf(1.f + __expf(-x)); }
; DI void swa_item(const P& p, int l, int item, unsigned char* smem) {
;     ...
;     lsum += __shfl_xor(lsum, 16); lsum += __shfl_xor(lsum, 32);
;     const float inv = __builtin_amdgcn_rcpf(lsum);
; #pragma unroll
;     for (int nt = 0; nt < 8; ++nt) {
;         const int dvb = 16 * nt + 4 * g;
;         const u32x2 gw = *(const u32x2*)(S + qrow * NP + C_SWA_G + 128 * hq + dvb);
;         const float g0 = lo16(gw.x), g1 = hi16(gw.x), g2 = lo16(gw.y), g3 = hi16(gw.y);
;         u32x2 o; o.x = pk2(ot[nt][0] * inv * siluf(g0), ot[nt][1] * inv * siluf(g1)); o.y = pk2(ot[nt][2] * inv * siluf(g2), ot[nt][3] * inv * siluf(g3));
;         *(u32x2*)(Y + qrow * DM + 1536 + 128 * hq + dvb) = o;
;     }
	v_mov_b32_e32 v20, v66
	v_mov_b32_e32 v21, v67
	v_lshlrev_b32_e32 v22, 16, v20
	v_and_b32_e32 v23, 0xffff0000, v20
	v_mul_f32_e32 v20, 0xbfb8aa3b, v22
	v_exp_f32_e32 v20, v20
	s_nop 0
	v_add_f32_e32 v20, 1.0, v20
	v_rcp_f32_e32 v24, v20
	v_mul_f32_e32 v20, 0xbfb8aa3b, v23
	v_exp_f32_e32 v20, v20
	s_nop 0
	v_add_f32_e32 v20, 1.0, v20
	v_rcp_f32_e32 v25, v20
	v_lshlrev_b32_e32 v20, 16, v21
	v_and_b32_e32 v21, 0xffff0000, v21
	v_pk_mul_f32 v[22:23], v[24:25], v[22:23]
	s_nop 0
	v_pk_mul_f32 v[16:17], v[16:17], v[22:23]
	s_nop 0
	v_cvt_pk_bf16_f32 v16, v16, v17
	v_mul_f32_e32 v17, 0xbfb8aa3b, v20
	v_exp_f32_e32 v17, v17
	s_nop 0
	v_add_f32_e32 v17, 1.0, v17
	v_rcp_f32_e32 v22, v17
	v_mul_f32_e32 v17, 0xbfb8aa3b, v21
	v_exp_f32_e32 v17, v17
	s_nop 0
	v_add_f32_e32 v17, 1.0, v17
	v_rcp_f32_e32 v23, v17
	s_nop 0
	v_pk_mul_f32 v[20:21], v[22:23], v[20:21]
	s_nop 0
	v_pk_mul_f32 v[18:19], v[18:19], v[20:21]
	s_nop 0
	v_cvt_pk_bf16_f32 v17, v18, v19
	global_store_dwordx2 v[30:31], v[16:17], off offset:96
	s_waitcnt vmcnt(7)
	v_mov_b32_e32 v16, v68
	v_mov_b32_e32 v17, v69
	v_lshlrev_b32_e32 v18, 16, v16
	v_and_b32_e32 v19, 0xffff0000, v16
	v_mul_f32_e32 v16, 0xbfb8aa3b, v18
	v_exp_f32_e32 v16, v16
	s_nop 0
	v_add_f32_e32 v16, 1.0, v16
	v_rcp_f32_e32 v20, v16
	v_mul_f32_e32 v16, 0xbfb8aa3b, v19
	v_exp_f32_e32 v16, v16
	s_nop 0
	v_add_f32_e32 v16, 1.0, v16
	v_rcp_f32_e32 v21, v16
	v_lshlrev_b32_e32 v16, 16, v17
	v_and_b32_e32 v17, 0xffff0000, v17
	v_pk_mul_f32 v[18:19], v[20:21], v[18:19]
	s_nop 0
	v_pk_mul_f32 v[12:13], v[12:13], v[18:19]
	s_nop 0
	v_cvt_pk_bf16_f32 v12, v12, v13
	v_mul_f32_e32 v13, 0xbfb8aa3b, v16
	v_exp_f32_e32 v13, v13
	s_nop 0
	v_add_f32_e32 v13, 1.0, v13
	v_rcp_f32_e32 v18, v13
	v_mul_f32_e32 v13, 0xbfb8aa3b, v17
	v_exp_f32_e32 v13, v13
	s_nop 0
	v_add_f32_e32 v13, 1.0, v13
	v_rcp_f32_e32 v19, v13
	s_nop 0
	v_pk_mul_f32 v[16:17], v[18:19], v[16:17]
	s_nop 0
	v_pk_mul_f32 v[14:15], v[14:15], v[16:17]
	s_nop 0
	v_cvt_pk_bf16_f32 v13, v14, v15
	global_store_dwordx2 v[30:31], v[12:13], off offset:128
	s_waitcnt vmcnt(7)
	v_mov_b32_e32 v12, v70
	v_mov_b32_e32 v13, v71
	v_lshlrev_b32_e32 v14, 16, v12
	v_and_b32_e32 v15, 0xffff0000, v12
	v_mul_f32_e32 v12, 0xbfb8aa3b, v14
	v_exp_f32_e32 v12, v12
	s_nop 0
	v_add_f32_e32 v12, 1.0, v12
	v_rcp_f32_e32 v16, v12
	v_mul_f32_e32 v12, 0xbfb8aa3b, v15
	v_exp_f32_e32 v12, v12
	s_nop 0
	v_add_f32_e32 v12, 1.0, v12
	v_rcp_f32_e32 v17, v12
	v_lshlrev_b32_e32 v12, 16, v13
	v_and_b32_e32 v13, 0xffff0000, v13
	v_pk_mul_f32 v[14:15], v[16:17], v[14:15]
	s_nop 0
	v_pk_mul_f32 v[8:9], v[8:9], v[14:15]
	s_nop 0
	v_cvt_pk_bf16_f32 v8, v8, v9
	v_mul_f32_e32 v9, 0xbfb8aa3b, v12
	v_exp_f32_e32 v9, v9
	s_nop 0
	v_add_f32_e32 v9, 1.0, v9
	v_rcp_f32_e32 v14, v9
	v_mul_f32_e32 v9, 0xbfb8aa3b, v13
	v_exp_f32_e32 v9, v9
	s_nop 0
	v_add_f32_e32 v9, 1.0, v9
	v_rcp_f32_e32 v15, v9
	s_nop 0
	v_pk_mul_f32 v[12:13], v[14:15], v[12:13]
	s_nop 0
	v_pk_mul_f32 v[10:11], v[10:11], v[12:13]
	s_nop 0
	v_cvt_pk_bf16_f32 v9, v10, v11
	global_store_dwordx2 v[30:31], v[8:9], off offset:160
	s_waitcnt vmcnt(7)
	v_mov_b32_e32 v8, v72
	v_mov_b32_e32 v9, v73
	v_lshlrev_b32_e32 v10, 16, v8
	v_and_b32_e32 v11, 0xffff0000, v8
	v_mul_f32_e32 v8, 0xbfb8aa3b, v10
	v_exp_f32_e32 v8, v8
	s_nop 0
	v_add_f32_e32 v8, 1.0, v8
	v_rcp_f32_e32 v12, v8
	v_mul_f32_e32 v8, 0xbfb8aa3b, v11
	v_exp_f32_e32 v8, v8
	s_nop 0
	v_add_f32_e32 v8, 1.0, v8
	v_rcp_f32_e32 v13, v8
	v_lshlrev_b32_e32 v8, 16, v9
	v_and_b32_e32 v9, 0xffff0000, v9
	v_pk_mul_f32 v[10:11], v[12:13], v[10:11]
	s_nop 0
	v_pk_mul_f32 v[4:5], v[4:5], v[10:11]
	s_nop 0
	v_cvt_pk_bf16_f32 v4, v4, v5
	v_mul_f32_e32 v5, 0xbfb8aa3b, v8
	v_exp_f32_e32 v5, v5
	s_nop 0
	v_add_f32_e32 v5, 1.0, v5
	v_rcp_f32_e32 v10, v5
	v_mul_f32_e32 v5, 0xbfb8aa3b, v9
	v_exp_f32_e32 v5, v5
	s_nop 0
	v_add_f32_e32 v5, 1.0, v5
	v_rcp_f32_e32 v11, v5
	s_nop 0
	v_pk_mul_f32 v[8:9], v[10:11], v[8:9]
	s_nop 0
	v_pk_mul_f32 v[6:7], v[6:7], v[8:9]
	s_nop 0
	v_cvt_pk_bf16_f32 v5, v6, v7
	global_store_dwordx2 v[30:31], v[4:5], off offset:192
	s_waitcnt vmcnt(7)
	v_mov_b32_e32 v4, v74
	v_mov_b32_e32 v5, v75
	v_lshlrev_b32_e32 v6, 16, v4
	v_and_b32_e32 v7, 0xffff0000, v4
	v_mul_f32_e32 v4, 0xbfb8aa3b, v6
	v_exp_f32_e32 v4, v4
	s_nop 0
	v_add_f32_e32 v4, 1.0, v4
	v_rcp_f32_e32 v8, v4
	v_mul_f32_e32 v4, 0xbfb8aa3b, v7
	v_exp_f32_e32 v4, v4
	s_nop 0
	v_add_f32_e32 v4, 1.0, v4
	v_rcp_f32_e32 v9, v4
	v_lshlrev_b32_e32 v4, 16, v5
	v_and_b32_e32 v5, 0xffff0000, v5
	v_pk_mul_f32 v[6:7], v[8:9], v[6:7]
	s_nop 0
	v_pk_mul_f32 v[0:1], v[0:1], v[6:7]
	s_nop 0
	v_cvt_pk_bf16_f32 v0, v0, v1
	v_mul_f32_e32 v1, 0xbfb8aa3b, v4
	v_exp_f32_e32 v1, v1
	s_nop 0
	v_add_f32_e32 v1, 1.0, v1
	v_rcp_f32_e32 v6, v1
	v_mul_f32_e32 v1, 0xbfb8aa3b, v5
	v_exp_f32_e32 v1, v1
	s_nop 0
	v_add_f32_e32 v1, 1.0, v1
	v_rcp_f32_e32 v7, v1
	s_nop 0
	v_pk_mul_f32 v[4:5], v[6:7], v[4:5]
	s_nop 0
	v_pk_mul_f32 v[2:3], v[2:3], v[4:5]
	s_nop 0
	v_cvt_pk_bf16_f32 v1, v2, v3
	global_store_dwordx2 v[30:31], v[0:1], off offset:224
	s_cbranch_scc1 .LBB0_385

; DI float lo16(unsigned u) { return __uint_as_float(u << 16); }
; DI float hi16(unsigned u) { return __uint_as_float(u & 0xFFFF0000u); }
; DI float siluf(float x) { return x * __builtin_amdgcn_rcpf(1.f + __expf(-x)); }
; DI void swa_item(const P& p, int l, int item, unsigned char* smem) {
;     ...
;     lsum += __shfl_xor(lsum, 16); lsum += __shfl_xor(lsum, 32);
;     const float inv = __builtin_amdgcn_rcpf(lsum);
; #pragma unroll
;     for (int nt = 0; nt < 8; ++nt) {
;         const int dvb = 16 * nt + 4 * g;
;         const u32x2 gw = *(const u32x2*)(S + qrow * NP + C_SWA_G + 128 * hq + dvb);
;         const float g0 = lo16(gw.x), g1 = hi16(gw.x), g2 = lo16(gw.y), g3 = hi16(gw.y);
;         u32x2 o; o.x = pk2(ot[nt][0] * inv * siluf(g0), ot[nt][1] * inv * siluf(g1)); o.y = pk2(ot[nt][2] * inv * siluf(g2), ot[nt][3] * inv * siluf(g3));
;         *(u32x2*)(Y + qrow * DM + 1536 + 128 * hq + dvb) = o;
;     }
.LBB0_432:
	v_cmp_lt_i32_e32 vcc, v105, v107
	s_waitcnt vmcnt(2)
	v_lshlrev_b64 v[34:35], 12, v[96:97]
	v_lshlrev_b64 v[30:31], 1, v[100:101]
	v_cndmask_b32_e32 v28, v59, v105, vcc
	v_cmp_lt_i32_e32 vcc, v109, v107
	v_lshl_add_u64 v[34:35], s[38:39], 0, v[34:35]
	v_mov_b32_e32 v107, v133
	v_lshl_add_u64 v[32:33], v[98:99], 0, v[30:31]
	v_lshl_add_u64 v[30:31], v[34:35], 0, v[30:31]
	v_lshlrev_b64 v[34:35], 1, v[106:107]
	s_waitcnt vmcnt(1)
	v_lshl_add_u64 v[36:37], v[32:33], 0, v[34:35]
	s_mov_b64 s[0:1], 0x3400
	v_lshl_add_u64 v[32:33], v[36:37], 0, s[0:1]
	s_movk_i32 s0, 0x3000
	v_cndmask_b32_e32 v29, v59, v109, vcc
	v_add_co_u32_e32 v36, vcc, s0, v36
	v_lshlrev_b32_e32 v28, 2, v28
	s_nop 0
	v_addc_co_u32_e32 v37, vcc, 0, v37, vcc
	global_load_dwordx2 v[36:37], v[36:37], off offset:1024
	global_load_dwordx2 v[62:63], v[32:33], off offset:32
	global_load_dwordx2 v[64:65], v[32:33], off offset:64
	global_load_dwordx2 v[66:67], v[32:33], off offset:96
	global_load_dwordx2 v[68:69], v[32:33], off offset:128
	global_load_dwordx2 v[70:71], v[32:33], off offset:160
	global_load_dwordx2 v[72:73], v[32:33], off offset:192
	global_load_dwordx2 v[74:75], v[32:33], off offset:224
	ds_bpermute_b32 v28, v28, v118
	v_lshlrev_b32_e32 v29, 2, v29
	v_lshl_add_u64 v[34:35], v[30:31], 0, v[34:35]
	s_mov_b64 s[0:1], 0xea3cc00
	v_lshl_add_u64 v[30:31], v[34:35], 0, s[0:1]
	s_waitcnt lgkmcnt(0)
	v_add_f32_e32 v28, v118, v28
	ds_bpermute_b32 v29, v29, v28
	s_mov_b32 s0, 0xea3c000
	v_add_co_u32_e32 v34, vcc, s0, v34
	s_add_i32 s51, s51, 12
	s_waitcnt lgkmcnt(0)
	v_add_f32_e32 v28, v28, v29
	v_rcp_f32_e32 v28, v28
	v_addc_co_u32_e32 v35, vcc, 0, v35, vcc
	s_cmp_ge_u32 s51, s21
	s_waitcnt vmcnt(7)
	v_lshlrev_b32_e32 v38, 16, v36
	v_mul_f32_e32 v29, 0xbfb8aa3b, v38
	v_exp_f32_e32 v29, v29
	v_and_b32_e32 v39, 0xffff0000, v36
	v_add_f32_e32 v29, 1.0, v29
	v_rcp_f32_e32 v40, v29
	v_pk_mul_f32 v[42:43], v[48:49], v[28:29] op_sel_hi:[1,0]
	v_mul_f32_e32 v29, 0xbfb8aa3b, v39
	v_exp_f32_e32 v29, v29
	s_nop 0
	v_add_f32_e32 v29, 1.0, v29
	v_rcp_f32_e32 v41, v29
	s_nop 0
	v_pk_mul_f32 v[38:39], v[40:41], v[38:39]
	s_nop 0
	v_pk_mul_f32 v[38:39], v[42:43], v[38:39]
	s_nop 0
	v_cvt_pk_bf16_f32 v36, v38, v39
	v_lshlrev_b32_e32 v38, 16, v37
	v_mul_f32_e32 v29, 0xbfb8aa3b, v38
	v_exp_f32_e32 v29, v29
	v_and_b32_e32 v39, 0xffff0000, v37
	v_add_f32_e32 v29, 1.0, v29
	v_rcp_f32_e32 v40, v29
	v_pk_mul_f32 v[42:43], v[50:51], v[28:29] op_sel_hi:[1,0]
	v_mul_f32_e32 v29, 0xbfb8aa3b, v39
	v_exp_f32_e32 v29, v29
	s_nop 0
	v_add_f32_e32 v29, 1.0, v29
	v_rcp_f32_e32 v41, v29
	s_nop 0
	v_pk_mul_f32 v[38:39], v[40:41], v[38:39]
	s_nop 0
	v_pk_mul_f32 v[38:39], v[42:43], v[38:39]
	s_nop 0
	v_cvt_pk_bf16_f32 v37, v38, v39
	global_store_dwordx2 v[34:35], v[36:37], off offset:3072
	s_waitcnt vmcnt(7)
	v_mov_b32_e32 v34, v62
	v_mov_b32_e32 v35, v63
	v_lshlrev_b32_e32 v36, 16, v34
	v_mul_f32_e32 v29, 0xbfb8aa3b, v36
	v_exp_f32_e32 v29, v29
	v_and_b32_e32 v37, 0xffff0000, v34
	v_lshlrev_b32_e32 v34, 16, v35
	v_and_b32_e32 v35, 0xffff0000, v35
	v_add_f32_e32 v29, 1.0, v29
	v_rcp_f32_e32 v38, v29
	v_pk_mul_f32 v[24:25], v[24:25], v[28:29] op_sel_hi:[1,0]
	v_mul_f32_e32 v29, 0xbfb8aa3b, v37
	v_exp_f32_e32 v29, v29
	s_nop 0
	v_add_f32_e32 v29, 1.0, v29
	v_rcp_f32_e32 v39, v29
	v_pk_mul_f32 v[26:27], v[26:27], v[28:29] op_sel_hi:[1,0]
	v_pk_mul_f32 v[20:21], v[20:21], v[28:29] op_sel_hi:[1,0]
	v_pk_mul_f32 v[22:23], v[22:23], v[28:29] op_sel_hi:[1,0]
	v_pk_mul_f32 v[36:37], v[38:39], v[36:37]
	v_pk_mul_f32 v[16:17], v[16:17], v[28:29] op_sel_hi:[1,0]
	v_pk_mul_f32 v[24:25], v[24:25], v[36:37]
	v_pk_mul_f32 v[18:19], v[18:19], v[28:29] op_sel_hi:[1,0]
	v_cvt_pk_bf16_f32 v24, v24, v25
	v_mul_f32_e32 v25, 0xbfb8aa3b, v34
	v_exp_f32_e32 v25, v25
	v_pk_mul_f32 v[12:13], v[12:13], v[28:29] op_sel_hi:[1,0]
	v_pk_mul_f32 v[14:15], v[14:15], v[28:29] op_sel_hi:[1,0]
	v_pk_mul_f32 v[8:9], v[8:9], v[28:29] op_sel_hi:[1,0]
	v_add_f32_e32 v25, 1.0, v25
	v_rcp_f32_e32 v36, v25
	v_mul_f32_e32 v25, 0xbfb8aa3b, v35
	v_exp_f32_e32 v25, v25
	v_pk_mul_f32 v[10:11], v[10:11], v[28:29] op_sel_hi:[1,0]
	v_pk_mul_f32 v[4:5], v[4:5], v[28:29] op_sel_hi:[1,0]
	v_pk_mul_f32 v[6:7], v[6:7], v[28:29] op_sel_hi:[1,0]
	v_add_f32_e32 v25, 1.0, v25
	v_rcp_f32_e32 v37, v25
	v_pk_mul_f32 v[0:1], v[0:1], v[28:29] op_sel_hi:[1,0]
	v_pk_mul_f32 v[2:3], v[2:3], v[28:29] op_sel_hi:[1,0]
	v_pk_mul_f32 v[34:35], v[36:37], v[34:35]
	s_nop 0
	v_pk_mul_f32 v[26:27], v[26:27], v[34:35]
	s_nop 0
	v_cvt_pk_bf16_f32 v25, v26, v27
	global_store_dwordx2 v[30:31], v[24:25], off offset:32
	s_waitcnt vmcnt(7)
	v_mov_b32_e32 v24, v64
	v_mov_b32_e32 v25, v65
	v_lshlrev_b32_e32 v26, 16, v24
	v_and_b32_e32 v27, 0xffff0000, v24
	v_mul_f32_e32 v24, 0xbfb8aa3b, v26
	v_exp_f32_e32 v24, v24
	s_nop 0
	v_add_f32_e32 v24, 1.0, v24
	v_rcp_f32_e32 v34, v24
	v_mul_f32_e32 v24, 0xbfb8aa3b, v27
	v_exp_f32_e32 v24, v24
	s_nop 0
	v_add_f32_e32 v24, 1.0, v24
	v_rcp_f32_e32 v35, v24
	v_lshlrev_b32_e32 v24, 16, v25
	v_and_b32_e32 v25, 0xffff0000, v25
	v_pk_mul_f32 v[26:27], v[34:35], v[26:27]
	s_nop 0
	v_pk_mul_f32 v[20:21], v[20:21], v[26:27]
	s_nop 0
	v_cvt_pk_bf16_f32 v20, v20, v21
	v_mul_f32_e32 v21, 0xbfb8aa3b, v24
	v_exp_f32_e32 v21, v21
	s_nop 0
	v_add_f32_e32 v21, 1.0, v21
	v_rcp_f32_e32 v26, v21
	v_mul_f32_e32 v21, 0xbfb8aa3b, v25
	v_exp_f32_e32 v21, v21
	s_nop 0
	v_add_f32_e32 v21, 1.0, v21
	v_rcp_f32_e32 v27, v21
	s_nop 0
	v_pk_mul_f32 v[24:25], v[26:27], v[24:25]
	s_nop 0
	v_pk_mul_f32 v[22:23], v[22:23], v[24:25]
	s_nop 0
	v_cvt_pk_bf16_f32 v21, v22, v23
	global_store_dwordx2 v[30:31], v[20:21], off offset:64
	s_waitcnt vmcnt(7)
; DI float lo16(unsigned u) { return __uint_as_float(u << 16); }
; DI float hi16(unsigned u) { return __uint_as_float(u & 0xFFFF0000u); }
; DI float siluf(float x) { return x * __builtin_amdgcn_rcpf(1.f + __expf(-x)); }
; DI void swa_item(const P& p, int l, int item, unsigned char* smem) {
;     ...
;     lsum += __shfl_xor(lsum, 16); lsum += __shfl_xor(lsum, 32);
;     const float inv = __builtin_amdgcn_rcpf(lsum);
; #pragma unroll
;     for (int nt = 0; nt < 8; ++nt) {
;         const int dvb = 16 * nt + 4 * g;
;         const u32x2 gw = *(const u32x2*)(S + qrow * NP + C_SWA_G + 128 * hq + dvb);
;         const float g0 = lo16(gw.x), g1 = hi16(gw.x), g2 = lo16(gw.y), g3 = hi16(gw.y);
;         u32x2 o; o.x = pk2(ot[nt][0] * inv * siluf(g0), ot[nt][1] * inv * siluf(g1)); o.y = pk2(ot[nt][2] * inv * siluf(g2), ot[nt][3] * inv * siluf(g3));
;         *(u32x2*)(Y + qrow * DM + 1536 + 128 * hq + dvb) = o;
;     }
	v_mov_b32_e32 v20, v66
	v_mov_b32_e32 v21, v67
	v_lshlrev_b32_e32 v22, 16, v20
	v_and_b32_e32 v23, 0xffff0000, v20
	v_mul_f32_e32 v20, 0xbfb8aa3b, v22
	v_exp_f32_e32 v20, v20
	s_nop 0
	v_add_f32_e32 v20, 1.0, v20
	v_rcp_f32_e32 v24, v20
	v_mul_f32_e32 v20, 0xbfb8aa3b, v23
	v_exp_f32_e32 v20, v20
	s_nop 0
	v_add_f32_e32 v20, 1.0, v20
	v_rcp_f32_e32 v25, v20
	v_lshlrev_b32_e32 v20, 16, v21
	v_and_b32_e32 v21, 0xffff0000, v21
	v_pk_mul_f32 v[22:23], v[24:25], v[22:23]
	s_nop 0
	v_pk_mul_f32 v[16:17], v[16:17], v[22:23]
	s_nop 0
	v_cvt_pk_bf16_f32 v16, v16, v17
	v_mul_f32_e32 v17, 0xbfb8aa3b, v20
	v_exp_f32_e32 v17, v17
	s_nop 0
	v_add_f32_e32 v17, 1.0, v17
	v_rcp_f32_e32 v22, v17
	v_mul_f32_e32 v17, 0xbfb8aa3b, v21
	v_exp_f32_e32 v17, v17
	s_nop 0
	v_add_f32_e32 v17, 1.0, v17
	v_rcp_f32_e32 v23, v17
	s_nop 0
	v_pk_mul_f32 v[20:21], v[22:23], v[20:21]
	s_nop 0
	v_pk_mul_f32 v[18:19], v[18:19], v[20:21]
	s_nop 0
	v_cvt_pk_bf16_f32 v17, v18, v19
	global_store_dwordx2 v[30:31], v[16:17], off offset:96
	s_waitcnt vmcnt(7)
	v_mov_b32_e32 v16, v68
	v_mov_b32_e32 v17, v69
	v_lshlrev_b32_e32 v18, 16, v16
	v_and_b32_e32 v19, 0xffff0000, v16
	v_mul_f32_e32 v16, 0xbfb8aa3b, v18
	v_exp_f32_e32 v16, v16
	s_nop 0
	v_add_f32_e32 v16, 1.0, v16
	v_rcp_f32_e32 v20, v16
	v_mul_f32_e32 v16, 0xbfb8aa3b, v19
	v_exp_f32_e32 v16, v16
	s_nop 0
	v_add_f32_e32 v16, 1.0, v16
	v_rcp_f32_e32 v21, v16
	v_lshlrev_b32_e32 v16, 16, v17
	v_and_b32_e32 v17, 0xffff0000, v17
	v_pk_mul_f32 v[18:19], v[20:21], v[18:19]
	s_nop 0
	v_pk_mul_f32 v[12:13], v[12:13], v[18:19]
	s_nop 0
	v_cvt_pk_bf16_f32 v12, v12, v13
	v_mul_f32_e32 v13, 0xbfb8aa3b, v16
	v_exp_f32_e32 v13, v13
	s_nop 0
	v_add_f32_e32 v13, 1.0, v13
	v_rcp_f32_e32 v18, v13
	v_mul_f32_e32 v13, 0xbfb8aa3b, v17
	v_exp_f32_e32 v13, v13
	s_nop 0
	v_add_f32_e32 v13, 1.0, v13
	v_rcp_f32_e32 v19, v13
	s_nop 0
	v_pk_mul_f32 v[16:17], v[18:19], v[16:17]
	s_nop 0
	v_pk_mul_f32 v[14:15], v[14:15], v[16:17]
	s_nop 0
	v_cvt_pk_bf16_f32 v13, v14, v15
	global_store_dwordx2 v[30:31], v[12:13], off offset:128
	s_waitcnt vmcnt(7)
	v_mov_b32_e32 v12, v70
	v_mov_b32_e32 v13, v71
	v_lshlrev_b32_e32 v14, 16, v12
	v_and_b32_e32 v15, 0xffff0000, v12
	v_mul_f32_e32 v12, 0xbfb8aa3b, v14
	v_exp_f32_e32 v12, v12
	s_nop 0
	v_add_f32_e32 v12, 1.0, v12
	v_rcp_f32_e32 v16, v12
	v_mul_f32_e32 v12, 0xbfb8aa3b, v15
	v_exp_f32_e32 v12, v12
	s_nop 0
	v_add_f32_e32 v12, 1.0, v12
	v_rcp_f32_e32 v17, v12
	v_lshlrev_b32_e32 v12, 16, v13
	v_and_b32_e32 v13, 0xffff0000, v13
	v_pk_mul_f32 v[14:15], v[16:17], v[14:15]
	s_nop 0
	v_pk_mul_f32 v[8:9], v[8:9], v[14:15]
	s_nop 0
	v_cvt_pk_bf16_f32 v8, v8, v9
	v_mul_f32_e32 v9, 0xbfb8aa3b, v12
	v_exp_f32_e32 v9, v9
	s_nop 0
	v_add_f32_e32 v9, 1.0, v9
	v_rcp_f32_e32 v14, v9
	v_mul_f32_e32 v9, 0xbfb8aa3b, v13
	v_exp_f32_e32 v9, v9
	s_nop 0
	v_add_f32_e32 v9, 1.0, v9
	v_rcp_f32_e32 v15, v9
	s_nop 0
	v_pk_mul_f32 v[12:13], v[14:15], v[12:13]
	s_nop 0
	v_pk_mul_f32 v[10:11], v[10:11], v[12:13]
	s_nop 0
	v_cvt_pk_bf16_f32 v9, v10, v11
	global_store_dwordx2 v[30:31], v[8:9], off offset:160
	s_waitcnt vmcnt(7)
	v_mov_b32_e32 v8, v72
	v_mov_b32_e32 v9, v73
	v_lshlrev_b32_e32 v10, 16, v8
	v_and_b32_e32 v11, 0xffff0000, v8
	v_mul_f32_e32 v8, 0xbfb8aa3b, v10
	v_exp_f32_e32 v8, v8
	s_nop 0
	v_add_f32_e32 v8, 1.0, v8
	v_rcp_f32_e32 v12, v8
	v_mul_f32_e32 v8, 0xbfb8aa3b, v11
	v_exp_f32_e32 v8, v8
	s_nop 0
	v_add_f32_e32 v8, 1.0, v8
	v_rcp_f32_e32 v13, v8
	v_lshlrev_b32_e32 v8, 16, v9
	v_and_b32_e32 v9, 0xffff0000, v9
	v_pk_mul_f32 v[10:11], v[12:13], v[10:11]
	s_nop 0
	v_pk_mul_f32 v[4:5], v[4:5], v[10:11]
	s_nop 0
	v_cvt_pk_bf16_f32 v4, v4, v5
	v_mul_f32_e32 v5, 0xbfb8aa3b, v8
	v_exp_f32_e32 v5, v5
	s_nop 0
	v_add_f32_e32 v5, 1.0, v5
	v_rcp_f32_e32 v10, v5
	v_mul_f32_e32 v5, 0xbfb8aa3b, v9
	v_exp_f32_e32 v5, v5
	s_nop 0
	v_add_f32_e32 v5, 1.0, v5
	v_rcp_f32_e32 v11, v5
	s_nop 0
	v_pk_mul_f32 v[8:9], v[10:11], v[8:9]
	s_nop 0
	v_pk_mul_f32 v[6:7], v[6:7], v[8:9]
	s_nop 0
	v_cvt_pk_bf16_f32 v5, v6, v7
	global_store_dwordx2 v[30:31], v[4:5], off offset:192
	s_waitcnt vmcnt(7)
	v_mov_b32_e32 v4, v74
	v_mov_b32_e32 v5, v75
	v_lshlrev_b32_e32 v6, 16, v4
	v_and_b32_e32 v7, 0xffff0000, v4
	v_mul_f32_e32 v4, 0xbfb8aa3b, v6
	v_exp_f32_e32 v4, v4
	s_nop 0
	v_add_f32_e32 v4, 1.0, v4
	v_rcp_f32_e32 v8, v4
	v_mul_f32_e32 v4, 0xbfb8aa3b, v7
	v_exp_f32_e32 v4, v4
	s_nop 0
	v_add_f32_e32 v4, 1.0, v4
	v_rcp_f32_e32 v9, v4
	v_lshlrev_b32_e32 v4, 16, v5
	v_and_b32_e32 v5, 0xffff0000, v5
	v_pk_mul_f32 v[6:7], v[8:9], v[6:7]
	s_nop 0
	v_pk_mul_f32 v[0:1], v[0:1], v[6:7]
	s_nop 0
	v_cvt_pk_bf16_f32 v0, v0, v1
	v_mul_f32_e32 v1, 0xbfb8aa3b, v4
	v_exp_f32_e32 v1, v1
	s_nop 0
	v_add_f32_e32 v1, 1.0, v1
	v_rcp_f32_e32 v6, v1
	v_mul_f32_e32 v1, 0xbfb8aa3b, v5
	v_exp_f32_e32 v1, v1
	s_nop 0
	v_add_f32_e32 v1, 1.0, v1
	v_rcp_f32_e32 v7, v1
	s_nop 0
	v_pk_mul_f32 v[4:5], v[6:7], v[4:5]
	s_nop 0
	v_pk_mul_f32 v[2:3], v[2:3], v[4:5]
	s_nop 0
	v_cvt_pk_bf16_f32 v1, v2, v3
	global_store_dwordx2 v[30:31], v[0:1], off offset:224
	s_cbranch_scc1 .LBB0_527
